# FUSED_OUT epilogues: 4 serialized sc1 slot loads issued together (C3, ABout, F3)
# baseline (speedup 1.0000x reference)
.LBB0_330:
	s_waitcnt vmcnt(0) lgkmcnt(0)
	s_barrier
	s_and_saveexec_b64 s[0:1], s[8:9]
	s_cbranch_execz .LBB0_332
	v_lshlrev_b64 v[118:119], 5, v[114:115]
	v_lshl_add_u64 v[118:119], s[48:49], 0, v[118:119]
	v_lshl_add_u64 v[114:115], v[114:115], 2, s[46:47]
	global_load_dwordx2 v[120:121], v[118:119], off sc1
	global_load_dwordx2 v[122:123], v[118:119], off offset:8 sc1
	global_load_dwordx2 v[124:125], v[118:119], off offset:16 sc1
	global_load_dwordx2 v[126:127], v[118:119], off offset:24 sc1
	global_load_dword v114, v[114:115], off
	s_waitcnt vmcnt(4)
	v_add_f32_e32 v117, v120, v121
	v_add_f32_e32 v117, 0, v117
	s_waitcnt vmcnt(3)
	v_add_f32_e32 v120, v122, v123
	v_add_f32_e32 v117, v117, v120
	s_waitcnt vmcnt(2)
	v_add_f32_e32 v120, v124, v125
	v_add_f32_e32 v117, v117, v120
	s_waitcnt vmcnt(1)
	v_add_f32_e32 v118, v126, v127
	v_add_f32_e32 v117, v117, v118
	s_waitcnt vmcnt(0)
	v_cvt_f32_u32_e32 v114, v114
	v_fmamk_f32 v114, v114, 0x33000000, v213
	v_rsq_f32_e32 v114, v114
	s_nop 0
	v_mul_f32_e32 v115, v114, v114
	v_mul_f32_e32 v115, v117, v115
	v_fmamk_f32 v115, v115, 0x3a000000, v213
	v_rsq_f32_e32 v115, v115
	s_nop 0
	v_mul_f32_e32 v114, v114, v115
	v_lshl_add_u32 v115, v116, 2, 0
	v_add_u32_e32 v115, 0x21c00, v115
	ds_write_b32 v115, v114

.LBB0_870:
	s_waitcnt vmcnt(0) lgkmcnt(0)
	s_barrier
	s_and_saveexec_b64 s[0:1], s[6:7]
	s_cbranch_execz .LBB0_872
	v_lshlrev_b64 v[106:107], 5, v[106:107]
	v_lshl_add_u64 v[106:107], s[40:41], 0, v[106:107]
	global_load_dwordx2 v[118:119], v[106:107], off sc1
	global_load_dwordx2 v[120:121], v[106:107], off offset:8 sc1
	global_load_dwordx2 v[122:123], v[106:107], off offset:16 sc1
	global_load_dwordx2 v[106:107], v[106:107], off offset:24 sc1
	s_waitcnt vmcnt(3)
	v_add_f32_e32 v117, v118, v119
	v_add_f32_e32 v117, 0, v117
	s_waitcnt vmcnt(2)
	v_add_f32_e32 v118, v120, v121
	v_add_f32_e32 v117, v117, v118
	s_waitcnt vmcnt(1)
	v_add_f32_e32 v118, v122, v123
	v_add_f32_e32 v117, v117, v118
	s_waitcnt vmcnt(0)
	v_add_f32_e32 v106, v106, v107
	v_add_f32_e32 v106, v117, v106
	v_fmamk_f32 v106, v106, 0x3a000000, v213
	v_rsq_f32_e32 v106, v106
	v_lshl_add_u32 v107, v116, 2, 0
	v_add_u32_e32 v107, 0x21c00, v107
	ds_write_b32 v107, v106

.LBB0_1200:
	s_waitcnt vmcnt(0) lgkmcnt(0)
	s_barrier
	s_and_saveexec_b64 s[0:1], s[6:7]
	s_cbranch_execz .LBB0_1202
	v_lshlrev_b64 v[110:111], 5, v[102:103]
	v_lshl_add_u64 v[110:111], s[46:47], 0, v[110:111]
	v_lshl_add_u64 v[102:103], v[102:103], 2, s[40:41]
	global_load_dwordx2 v[112:113], v[110:111], off sc1
	global_load_dwordx2 v[114:115], v[110:111], off offset:8 sc1
	global_load_dwordx2 v[116:117], v[110:111], off offset:16 sc1
	global_load_dwordx2 v[118:119], v[110:111], off offset:24 sc1
	global_load_dword v102, v[102:103], off
	s_waitcnt vmcnt(4)
	v_add_f32_e32 v109, v112, v113
	v_add_f32_e32 v109, 0, v109
	s_waitcnt vmcnt(3)
	v_add_f32_e32 v112, v114, v115
	v_add_f32_e32 v109, v109, v112
	s_waitcnt vmcnt(2)
	v_add_f32_e32 v112, v116, v117
	v_add_f32_e32 v109, v109, v112
	s_waitcnt vmcnt(1)
	v_add_f32_e32 v110, v118, v119
	v_add_f32_e32 v109, v109, v110
	s_waitcnt vmcnt(0)
	v_cvt_f32_u32_e32 v102, v102
	v_fmamk_f32 v102, v102, 0x33000000, v213
	v_rsq_f32_e32 v102, v102
	s_nop 0
	v_mul_f32_e32 v103, v102, v102
	v_mul_f32_e32 v103, v109, v103
	v_fmamk_f32 v103, v103, 0x3a000000, v213
	v_rsq_f32_e32 v103, v103
	s_nop 0
	v_mul_f32_e32 v102, v102, v103
	v_lshl_add_u32 v103, v108, 2, 0
	v_add_u32_e32 v103, 0x21c00, v103
	ds_write_b32 v103, v102
